# attention: lazy softmax rescale (only when row max grows by >8 log2 units), on top of merge-loop wait hoist
# speedup vs baseline: 1.0101x; 1.0030x over previous
.LBB0_335:
	v_max_f32_e32 v0, v91, v91
	v_max_f32_e32 v74, v90, v90
	v_max_f32_e32 v0, v74, v0
	v_max3_f32 v0, v0, v188, v189
	v_max3_f32 v0, v0, v86, v87
	v_max3_f32 v0, v0, v186, v187
	v_max3_f32 v0, v0, v88, v89
	v_max3_f32 v0, v0, v92, v93
	v_max3_f32 v0, v0, v84, v85
	v_max3_f32 v0, v0, v96, v97
	v_max3_f32 v0, v0, v66, v67
	v_max3_f32 v0, v0, v94, v95
	v_max3_f32 v0, v0, v70, v71
	v_max3_f32 v0, v0, v82, v83
	v_max3_f32 v0, v0, v72, v73
	v_max3_f32 v0, v0, v76, v77
	v_max3_f32 v0, v0, v68, v69
	v_max3_f32 v0, v0, v80, v81
	ds_bpermute_b32 v74, v211, v0
	s_waitcnt lgkmcnt(0)
	v_max_f32_e32 v74, v74, v74
	v_max_f32_e32 v0, v0, v74
	v_mul_f32_e32 v0, v210, v0
	v_sub_f32_e32 v75, v0, v217
	v_cmp_lt_f32_e32 vcc, 0x41000000, v75
	s_nop 1
	v_cndmask_b32_e32 v74, v217, v0, vcc
	v_sub_f32_e32 v0, v217, v74
	v_exp_f32_e32 v0, v0
	s_cbranch_vccz .LBB0_337
	v_pk_mul_f32 v[64:65], v[64:65], v[0:1] op_sel_hi:[1,0]
	v_pk_mul_f32 v[62:63], v[62:63], v[0:1] op_sel_hi:[1,0]
	v_pk_mul_f32 v[60:61], v[60:61], v[0:1] op_sel_hi:[1,0]
	v_pk_mul_f32 v[58:59], v[58:59], v[0:1] op_sel_hi:[1,0]
	v_pk_mul_f32 v[56:57], v[56:57], v[0:1] op_sel_hi:[1,0]
	v_pk_mul_f32 v[54:55], v[54:55], v[0:1] op_sel_hi:[1,0]
	v_pk_mul_f32 v[52:53], v[52:53], v[0:1] op_sel_hi:[1,0]
	v_pk_mul_f32 v[50:51], v[50:51], v[0:1] op_sel_hi:[1,0]
	v_pk_mul_f32 v[48:49], v[48:49], v[0:1] op_sel_hi:[1,0]
	v_pk_mul_f32 v[46:47], v[46:47], v[0:1] op_sel_hi:[1,0]
	v_pk_mul_f32 v[44:45], v[44:45], v[0:1] op_sel_hi:[1,0]
	v_pk_mul_f32 v[42:43], v[42:43], v[0:1] op_sel_hi:[1,0]
	v_pk_mul_f32 v[40:41], v[40:41], v[0:1] op_sel_hi:[1,0]
	v_pk_mul_f32 v[38:39], v[38:39], v[0:1] op_sel_hi:[1,0]
	v_pk_mul_f32 v[36:37], v[36:37], v[0:1] op_sel_hi:[1,0]
	v_pk_mul_f32 v[34:35], v[34:35], v[0:1] op_sel_hi:[1,0]
	v_pk_mul_f32 v[32:33], v[32:33], v[0:1] op_sel_hi:[1,0]
	v_pk_mul_f32 v[30:31], v[30:31], v[0:1] op_sel_hi:[1,0]
	v_pk_mul_f32 v[28:29], v[28:29], v[0:1] op_sel_hi:[1,0]
	v_pk_mul_f32 v[26:27], v[26:27], v[0:1] op_sel_hi:[1,0]
	v_pk_mul_f32 v[24:25], v[24:25], v[0:1] op_sel_hi:[1,0]
	v_pk_mul_f32 v[22:23], v[22:23], v[0:1] op_sel_hi:[1,0]
	v_pk_mul_f32 v[20:21], v[20:21], v[0:1] op_sel_hi:[1,0]
	v_pk_mul_f32 v[18:19], v[18:19], v[0:1] op_sel_hi:[1,0]
	v_pk_mul_f32 v[16:17], v[16:17], v[0:1] op_sel_hi:[1,0]
	v_pk_mul_f32 v[14:15], v[14:15], v[0:1] op_sel_hi:[1,0]
	v_pk_mul_f32 v[12:13], v[12:13], v[0:1] op_sel_hi:[1,0]
	v_pk_mul_f32 v[10:11], v[10:11], v[0:1] op_sel_hi:[1,0]
	v_pk_mul_f32 v[8:9], v[8:9], v[0:1] op_sel_hi:[1,0]
	v_pk_mul_f32 v[6:7], v[6:7], v[0:1] op_sel_hi:[1,0]
	v_pk_mul_f32 v[4:5], v[4:5], v[0:1] op_sel_hi:[1,0]
	v_pk_mul_f32 v[2:3], v[2:3], v[0:1] op_sel_hi:[1,0]
